# plus MLA up-projection epilogue: the eight serial SSQ loads issued together
# speedup vs baseline: 1.0035x; 1.0035x over previous
.LBB0_791:
	s_lshl_b32 s5, s26, 8
	v_mbcnt_lo_u32_b32 v128, -1, 0
	v_mbcnt_hi_u32_b32 v128, -1, v128
	s_add_i32 s5, s5, s64
	v_and_or_b32 v138, v128, 15, s5
	s_lshl_b32 s5, s24, 8
	v_ashrrev_i32_e32 v128, 1, v128
	v_and_b32_e32 v128, -8, v128
	s_or_b32 s5, s5, s68
	v_add_u32_e32 v130, s5, v128
	s_lshl_b32 s5, s25, 10
	s_addk_i32 s5, 0xc00
	s_cmp_eq_u32 s25, 0
	v_readlane_b32 s15, v255, 12
	s_cselect_b32 s15, s15, 0
	s_lshl_b32 s28, s25, 1
	v_add_u32_e32 v128, s15, v138
	v_ashrrev_i32_e32 v129, 31, v128
	v_lshl_add_u64 v[128:129], v[128:129], 4, s[12:13]
	s_ashr_i32 s29, s28, 31
	v_lshl_add_u64 v[128:129], s[28:29], 2, v[128:129]
	global_load_dwordx2 v[142:143], v[128:129], off
	global_load_dwordx2 v[146:147], v[128:129], off offset:256
	global_load_dwordx2 v[148:149], v[128:129], off offset:512
	global_load_dwordx2 v[150:151], v[128:129], off offset:768
	global_load_dwordx2 v[152:153], v[128:129], off offset:2048
	global_load_dwordx2 v[154:155], v[128:129], off offset:2304
	global_load_dwordx2 v[156:157], v[128:129], off offset:2560
	global_load_dwordx2 v[158:159], v[128:129], off offset:2816
	s_ashr_i32 s15, s25, 31
	s_mul_hi_u32 s17, s10, s25
	s_mul_i32 s15, s10, s15
	s_add_i32 s15, s17, s15
	s_mul_i32 s17, s11, s25
	s_add_i32 s29, s15, s17
	s_mul_i32 s28, s10, s25
	s_lshl_b64 s[24:25], s[28:29], 1
	s_add_u32 s24, s74, s24
	v_ashrrev_i32_e32 v131, 31, v130
	s_addc_u32 s25, s78, s25
	v_mad_i64_i32 v[140:141], s[28:29], v138, s5, 0
	v_lshl_add_u64 v[140:141], v[140:141], 1, s[24:25]
	v_lshlrev_b64 v[130:131], 1, v[130:131]
	v_lshl_add_u64 v[140:141], v[140:141], 0, v[130:131]
	s_and_b64 vcc, exec, s[8:9]
	s_waitcnt vmcnt(0)
	v_add_f32_e32 v139, v142, v143
	v_fmamk_f32 v139, v139, 0x3b000000, v198
	v_rsq_f32_e32 v142, v139
	s_nop 0
	v_pk_mul_f32 v[126:127], v[126:127], v[142:143] op_sel_hi:[1,0]
	v_pk_mul_f32 v[124:125], v[124:125], v[142:143] op_sel_hi:[1,0]
	v_pk_mul_f32 v[144:145], v[122:123], v[142:143] op_sel_hi:[1,0]
	v_pk_mul_f32 v[122:123], v[120:121], v[142:143] op_sel_hi:[1,0]
	v_cvt_pk_bf16_f32 v120, v124, v125
	v_cvt_pk_bf16_f32 v121, v126, v127
	v_pk_mul_f32 v[118:119], v[118:119], v[142:143] op_sel_hi:[1,0]
	v_cvt_pk_bf16_f32 v122, v122, v123
	v_cvt_pk_bf16_f32 v123, v144, v145
	global_store_dwordx4 v[140:141], v[120:123], off
	v_pk_mul_f32 v[116:117], v[116:117], v[142:143] op_sel_hi:[1,0]
	s_nop 0
	v_pk_mul_f32 v[120:121], v[114:115], v[142:143] op_sel_hi:[1,0]
	v_pk_mul_f32 v[114:115], v[112:113], v[142:143] op_sel_hi:[1,0]
	v_cvt_pk_bf16_f32 v112, v116, v117
	v_cvt_pk_bf16_f32 v113, v118, v119
	s_nop 0
	v_cvt_pk_bf16_f32 v114, v114, v115
	v_cvt_pk_bf16_f32 v115, v120, v121
	global_store_dwordx4 v[140:141], v[112:115], off offset:256
	s_nop 0
	s_nop 0
	v_or_b32_e32 v112, 16, v138
	v_mad_i64_i32 v[112:113], s[28:29], v112, s5, 0
	v_lshl_add_u64 v[112:113], v[112:113], 1, s[24:25]
	v_lshl_add_u64 v[112:113], v[112:113], 0, v[130:131]
	v_add_f32_e32 v114, v146, v147
	v_fmamk_f32 v114, v114, 0x3b000000, v198
	v_rsq_f32_e32 v114, v114
	s_nop 0
	v_pk_mul_f32 v[110:111], v[110:111], v[114:115] op_sel_hi:[1,0]
	v_pk_mul_f32 v[108:109], v[108:109], v[114:115] op_sel_hi:[1,0]
	v_pk_mul_f32 v[116:117], v[106:107], v[114:115] op_sel_hi:[1,0]
	v_pk_mul_f32 v[106:107], v[104:105], v[114:115] op_sel_hi:[1,0]
	v_cvt_pk_bf16_f32 v104, v108, v109
	v_cvt_pk_bf16_f32 v105, v110, v111
	v_pk_mul_f32 v[102:103], v[102:103], v[114:115] op_sel_hi:[1,0]
	v_cvt_pk_bf16_f32 v106, v106, v107
	v_cvt_pk_bf16_f32 v107, v116, v117
	global_store_dwordx4 v[112:113], v[104:107], off
	v_pk_mul_f32 v[100:101], v[100:101], v[114:115] op_sel_hi:[1,0]
	s_nop 0
	v_pk_mul_f32 v[104:105], v[98:99], v[114:115] op_sel_hi:[1,0]
	v_pk_mul_f32 v[98:99], v[96:97], v[114:115] op_sel_hi:[1,0]
	v_cvt_pk_bf16_f32 v96, v100, v101
	v_cvt_pk_bf16_f32 v97, v102, v103
	s_nop 0
	v_cvt_pk_bf16_f32 v98, v98, v99
	v_cvt_pk_bf16_f32 v99, v104, v105
	global_store_dwordx4 v[112:113], v[96:99], off offset:256
	s_nop 0
	s_nop 0
	v_or_b32_e32 v96, 32, v138
	v_mad_i64_i32 v[96:97], s[28:29], v96, s5, 0
	v_lshl_add_u64 v[96:97], v[96:97], 1, s[24:25]
	v_lshl_add_u64 v[96:97], v[96:97], 0, v[130:131]
	v_add_f32_e32 v98, v148, v149
	v_fmamk_f32 v98, v98, 0x3b000000, v198
	v_rsq_f32_e32 v98, v98
	s_nop 0
	v_pk_mul_f32 v[94:95], v[94:95], v[98:99] op_sel_hi:[1,0]
	v_pk_mul_f32 v[92:93], v[92:93], v[98:99] op_sel_hi:[1,0]
	v_pk_mul_f32 v[100:101], v[90:91], v[98:99] op_sel_hi:[1,0]
	v_pk_mul_f32 v[90:91], v[88:89], v[98:99] op_sel_hi:[1,0]
	v_cvt_pk_bf16_f32 v88, v92, v93
	v_cvt_pk_bf16_f32 v89, v94, v95
	v_pk_mul_f32 v[86:87], v[86:87], v[98:99] op_sel_hi:[1,0]
	v_cvt_pk_bf16_f32 v90, v90, v91
	v_cvt_pk_bf16_f32 v91, v100, v101
	global_store_dwordx4 v[96:97], v[88:91], off
	v_pk_mul_f32 v[84:85], v[84:85], v[98:99] op_sel_hi:[1,0]
	s_nop 0
	v_pk_mul_f32 v[88:89], v[82:83], v[98:99] op_sel_hi:[1,0]
	v_pk_mul_f32 v[82:83], v[80:81], v[98:99] op_sel_hi:[1,0]
	v_cvt_pk_bf16_f32 v80, v84, v85
	v_cvt_pk_bf16_f32 v81, v86, v87
	s_nop 0
	v_cvt_pk_bf16_f32 v82, v82, v83
	v_cvt_pk_bf16_f32 v83, v88, v89
	global_store_dwordx4 v[96:97], v[80:83], off offset:256
	s_nop 0
	s_nop 0
	v_or_b32_e32 v80, 48, v138
	v_mad_i64_i32 v[80:81], s[28:29], v80, s5, 0
	v_lshl_add_u64 v[80:81], v[80:81], 1, s[24:25]
	v_lshl_add_u64 v[80:81], v[80:81], 0, v[130:131]
	v_add_f32_e32 v82, v150, v151
	v_fmamk_f32 v82, v82, 0x3b000000, v198
	v_rsq_f32_e32 v82, v82
	s_nop 0
	v_pk_mul_f32 v[78:79], v[78:79], v[82:83] op_sel_hi:[1,0]
	v_pk_mul_f32 v[76:77], v[76:77], v[82:83] op_sel_hi:[1,0]
	v_pk_mul_f32 v[84:85], v[74:75], v[82:83] op_sel_hi:[1,0]
	v_pk_mul_f32 v[74:75], v[72:73], v[82:83] op_sel_hi:[1,0]
	v_cvt_pk_bf16_f32 v72, v76, v77
	v_cvt_pk_bf16_f32 v73, v78, v79
	v_pk_mul_f32 v[70:71], v[70:71], v[82:83] op_sel_hi:[1,0]
	v_cvt_pk_bf16_f32 v74, v74, v75
	v_cvt_pk_bf16_f32 v75, v84, v85
	global_store_dwordx4 v[80:81], v[72:75], off
	v_pk_mul_f32 v[68:69], v[68:69], v[82:83] op_sel_hi:[1,0]
	s_nop 0
	v_pk_mul_f32 v[72:73], v[66:67], v[82:83] op_sel_hi:[1,0]
	v_pk_mul_f32 v[66:67], v[64:65], v[82:83] op_sel_hi:[1,0]
	v_cvt_pk_bf16_f32 v64, v68, v69
	v_cvt_pk_bf16_f32 v65, v70, v71
	s_nop 0
	v_cvt_pk_bf16_f32 v66, v66, v67
	v_cvt_pk_bf16_f32 v67, v72, v73
	global_store_dwordx4 v[80:81], v[64:67], off offset:256
	s_nop 0
	s_nop 0
	v_add_u32_e32 v64, 0x80, v138
	v_mad_i64_i32 v[64:65], s[28:29], v64, s5, 0
	v_lshl_add_u64 v[64:65], v[64:65], 1, s[24:25]
	v_lshl_add_u64 v[64:65], v[64:65], 0, v[130:131]
	v_add_f32_e32 v66, v152, v153
	v_fmamk_f32 v66, v66, 0x3b000000, v198
	v_rsq_f32_e32 v66, v66
	s_nop 0
	v_pk_mul_f32 v[62:63], v[62:63], v[66:67] op_sel_hi:[1,0]
	v_pk_mul_f32 v[60:61], v[60:61], v[66:67] op_sel_hi:[1,0]
	v_pk_mul_f32 v[68:69], v[58:59], v[66:67] op_sel_hi:[1,0]
	v_pk_mul_f32 v[58:59], v[56:57], v[66:67] op_sel_hi:[1,0]
	v_cvt_pk_bf16_f32 v56, v60, v61
	v_cvt_pk_bf16_f32 v57, v62, v63
	v_pk_mul_f32 v[54:55], v[54:55], v[66:67] op_sel_hi:[1,0]
	v_cvt_pk_bf16_f32 v58, v58, v59
	v_cvt_pk_bf16_f32 v59, v68, v69
	global_store_dwordx4 v[64:65], v[56:59], off
	v_pk_mul_f32 v[52:53], v[52:53], v[66:67] op_sel_hi:[1,0]
	s_nop 0
	v_pk_mul_f32 v[56:57], v[50:51], v[66:67] op_sel_hi:[1,0]
	v_pk_mul_f32 v[50:51], v[48:49], v[66:67] op_sel_hi:[1,0]
	v_cvt_pk_bf16_f32 v48, v52, v53
	v_cvt_pk_bf16_f32 v49, v54, v55
	s_nop 0
	v_cvt_pk_bf16_f32 v50, v50, v51
	v_cvt_pk_bf16_f32 v51, v56, v57
	global_store_dwordx4 v[64:65], v[48:51], off offset:256
	s_nop 0
	s_nop 0
	v_add_u32_e32 v48, 0x90, v138
	v_mad_i64_i32 v[48:49], s[28:29], v48, s5, 0
	v_lshl_add_u64 v[48:49], v[48:49], 1, s[24:25]
	v_lshl_add_u64 v[48:49], v[48:49], 0, v[130:131]
	v_add_f32_e32 v50, v154, v155
	v_fmamk_f32 v50, v50, 0x3b000000, v198
	v_rsq_f32_e32 v50, v50
	s_nop 0
	v_pk_mul_f32 v[46:47], v[46:47], v[50:51] op_sel_hi:[1,0]
	v_pk_mul_f32 v[44:45], v[44:45], v[50:51] op_sel_hi:[1,0]
	v_pk_mul_f32 v[52:53], v[42:43], v[50:51] op_sel_hi:[1,0]
	v_pk_mul_f32 v[42:43], v[40:41], v[50:51] op_sel_hi:[1,0]
	v_cvt_pk_bf16_f32 v40, v44, v45
	v_cvt_pk_bf16_f32 v41, v46, v47
	v_pk_mul_f32 v[38:39], v[38:39], v[50:51] op_sel_hi:[1,0]
	v_cvt_pk_bf16_f32 v42, v42, v43
	v_cvt_pk_bf16_f32 v43, v52, v53
	global_store_dwordx4 v[48:49], v[40:43], off
	v_pk_mul_f32 v[36:37], v[36:37], v[50:51] op_sel_hi:[1,0]
	s_nop 0
	v_pk_mul_f32 v[40:41], v[34:35], v[50:51] op_sel_hi:[1,0]
	v_pk_mul_f32 v[34:35], v[32:33], v[50:51] op_sel_hi:[1,0]
	v_cvt_pk_bf16_f32 v32, v36, v37
	v_cvt_pk_bf16_f32 v33, v38, v39
	s_nop 0
	v_cvt_pk_bf16_f32 v34, v34, v35
	v_cvt_pk_bf16_f32 v35, v40, v41
	global_store_dwordx4 v[48:49], v[32:35], off offset:256
	s_nop 0
	s_nop 0
	v_add_u32_e32 v32, 0xa0, v138
	v_mad_i64_i32 v[32:33], s[28:29], v32, s5, 0
	v_lshl_add_u64 v[32:33], v[32:33], 1, s[24:25]
	v_lshl_add_u64 v[32:33], v[32:33], 0, v[130:131]
	v_add_f32_e32 v34, v156, v157
	v_fmamk_f32 v34, v34, 0x3b000000, v198
	v_rsq_f32_e32 v34, v34
	s_nop 0
	v_pk_mul_f32 v[30:31], v[30:31], v[34:35] op_sel_hi:[1,0]
	v_pk_mul_f32 v[28:29], v[28:29], v[34:35] op_sel_hi:[1,0]
	v_pk_mul_f32 v[36:37], v[26:27], v[34:35] op_sel_hi:[1,0]
	v_pk_mul_f32 v[26:27], v[24:25], v[34:35] op_sel_hi:[1,0]
	v_cvt_pk_bf16_f32 v24, v28, v29
	v_cvt_pk_bf16_f32 v25, v30, v31
	v_pk_mul_f32 v[22:23], v[22:23], v[34:35] op_sel_hi:[1,0]
	v_cvt_pk_bf16_f32 v26, v26, v27
	v_cvt_pk_bf16_f32 v27, v36, v37
	global_store_dwordx4 v[32:33], v[24:27], off
	v_pk_mul_f32 v[20:21], v[20:21], v[34:35] op_sel_hi:[1,0]
	s_nop 0
	v_pk_mul_f32 v[24:25], v[18:19], v[34:35] op_sel_hi:[1,0]
	v_pk_mul_f32 v[18:19], v[16:17], v[34:35] op_sel_hi:[1,0]
	v_cvt_pk_bf16_f32 v16, v20, v21
	v_cvt_pk_bf16_f32 v17, v22, v23
	s_nop 0
	v_cvt_pk_bf16_f32 v18, v18, v19
	v_cvt_pk_bf16_f32 v19, v24, v25
	global_store_dwordx4 v[32:33], v[16:19], off offset:256
	s_nop 0
	s_nop 0
	v_add_u32_e32 v16, 0xb0, v138
	v_mad_i64_i32 v[16:17], s[28:29], v16, s5, 0
	v_lshl_add_u64 v[16:17], v[16:17], 1, s[24:25]
	v_lshl_add_u64 v[16:17], v[16:17], 0, v[130:131]
	s_mov_b64 s[24:25], -1
	v_add_f32_e32 v18, v158, v159
	v_fmamk_f32 v18, v18, 0x3b000000, v198
	v_rsq_f32_e32 v18, v18
	s_nop 0
	v_pk_mul_f32 v[14:15], v[14:15], v[18:19] op_sel_hi:[1,0]
	v_pk_mul_f32 v[12:13], v[12:13], v[18:19] op_sel_hi:[1,0]
	v_pk_mul_f32 v[20:21], v[10:11], v[18:19] op_sel_hi:[1,0]
	v_pk_mul_f32 v[10:11], v[8:9], v[18:19] op_sel_hi:[1,0]
	v_cvt_pk_bf16_f32 v8, v12, v13
	v_cvt_pk_bf16_f32 v9, v14, v15
	v_pk_mul_f32 v[6:7], v[6:7], v[18:19] op_sel_hi:[1,0]
	v_cvt_pk_bf16_f32 v10, v10, v11
	v_cvt_pk_bf16_f32 v11, v20, v21
	global_store_dwordx4 v[16:17], v[8:11], off
	v_pk_mul_f32 v[4:5], v[4:5], v[18:19] op_sel_hi:[1,0]
	s_nop 0
	v_pk_mul_f32 v[8:9], v[2:3], v[18:19] op_sel_hi:[1,0]
	v_pk_mul_f32 v[2:3], v[0:1], v[18:19] op_sel_hi:[1,0]
	v_cvt_pk_bf16_f32 v0, v4, v5
	v_cvt_pk_bf16_f32 v1, v6, v7
	s_nop 0
	v_cvt_pk_bf16_f32 v2, v2, v3
	v_cvt_pk_bf16_f32 v3, v8, v9
	global_store_dwordx4 v[16:17], v[0:3], off offset:256
	s_cbranch_vccnz .LBB0_776
	s_and_b64 vcc, exec, s[6:7]
	s_cbranch_vccnz .LBB0_775
	s_barrier
	s_branch .LBB0_775
